# baseline (speedup 1.0000x reference)
.LBB0_452:
	s_lshl_b32 s2, s12, 8
	s_add_i32 s2, s2, s64
	v_add_u32_e32 v136, s2, v134
	v_readlane_b32 s2, v251, 16
	v_ashrrev_i32_e32 v137, 31, v136
	v_readlane_b32 s3, v251, 17
	v_readlane_b32 s96, v254, 54
	v_readlane_b32 s72, v254, 56
	v_lshl_add_u32 v156, v135, 4, v136
	v_ashrrev_i32_e32 v157, 31, v156
	v_lshl_add_u64 v[154:155], v[156:157], 2, s[2:3]
	global_load_dword v150, v[154:155], off
	global_load_dword v142, v[154:155], off offset:512
	s_cmp_gt_i32 s43, 1
	s_mov_b64 s[52:53], -1
	v_readlane_b32 s97, v254, 55
	v_readlane_b32 s73, v254, 57
	s_waitcnt vmcnt(0)
	v_mov_b32_e32 v148, v150
	v_mov_b32_e32 v140, v142
	s_nop 1
	v_permlane16_swap_b32_e32 v150, v148
	v_permlane16_swap_b32_e32 v142, v140
	v_mov_b32_e32 v146, v150
	v_mov_b32_e32 v144, v148
	v_mov_b32_e32 v138, v142
	v_mov_b32_e32 v134, v140
	s_nop 1
	v_permlane32_swap_b32_e32 v150, v146
	v_permlane32_swap_b32_e32 v148, v144
	v_permlane32_swap_b32_e32 v142, v138
	v_permlane32_swap_b32_e32 v140, v134
	s_nop 0
	v_pk_mul_f32 v[128:129], v[128:129], v[150:151] op_sel_hi:[1,0]
	v_pk_mul_f32 v[126:127], v[126:127], v[150:151] op_sel_hi:[1,0]
	v_pk_mul_f32 v[124:125], v[124:125], v[150:151] op_sel_hi:[1,0]
	v_pk_mul_f32 v[122:123], v[122:123], v[150:151] op_sel_hi:[1,0]
	s_cbranch_scc0 .LBB0_454
	v_mul_f32_e32 v149, 0xbfb8aa3b, v129
	v_mul_f32_e32 v137, 0xbfb8aa3b, v126
	v_mul_f32_e32 v139, 0xbfb8aa3b, v122
	v_mul_f32_e32 v141, 0xbfb8aa3b, v127
	v_mul_f32_e32 v143, 0xbfb8aa3b, v123
	v_mul_f32_e32 v145, 0xbfb8aa3b, v128
	v_mul_f32_e32 v147, 0xbfb8aa3b, v124
	v_exp_f32_e32 v149, v149
	v_mul_f32_e32 v151, 0xbfb8aa3b, v125
	v_exp_f32_e32 v137, v137
	v_exp_f32_e32 v139, v139
	v_exp_f32_e32 v141, v141
	v_exp_f32_e32 v143, v143
	v_exp_f32_e32 v145, v145
	v_exp_f32_e32 v147, v147
	v_exp_f32_e32 v151, v151
	v_add_f32_e32 v149, 1.0, v149
	v_add_f32_e32 v137, 1.0, v137
	v_add_f32_e32 v139, 1.0, v139
	v_add_f32_e32 v141, 1.0, v141
	v_add_f32_e32 v143, 1.0, v143
	v_add_f32_e32 v145, 1.0, v145
	v_add_f32_e32 v147, 1.0, v147
	v_rcp_f32_e32 v154, v149
	v_add_f32_e32 v149, 1.0, v151
	v_rcp_f32_e32 v137, v137
	v_rcp_f32_e32 v139, v139
	v_rcp_f32_e32 v141, v141
	v_rcp_f32_e32 v143, v143
	v_rcp_f32_e32 v145, v145
	v_rcp_f32_e32 v147, v147
	v_rcp_f32_e32 v149, v149
	s_mov_b64 s[52:53], 0

.LBB0_566:
	s_lshl_b32 s2, s13, 8
	s_add_i32 s2, s2, s64
	v_add_u32_e32 v132, s2, v132
	v_readlane_b32 s2, v251, 16
	v_ashrrev_i32_e32 v133, 31, v132
	v_readlane_b32 s3, v251, 17
	s_cmp_gt_i32 s43, 1
	s_mov_b64 s[52:53], -1
	v_lshl_add_u32 v146, v144, 4, v132
	v_ashrrev_i32_e32 v147, 31, v146
	v_lshl_add_u64 v[134:135], v[146:147], 2, s[2:3]
	global_load_dword v145, v[134:135], off
	global_load_dword v140, v[134:135], off offset:512
	v_mov_b32_e32 v227, 0x358637bd
	v_mov_b32_e32 v228, 0x3c0881c4
	v_mov_b32_e32 v229, 0xbab64f3b
	v_mov_b32_e32 v230, 0x41b17218
	v_mov_b32_e32 v231, 0x3f80
	v_not_b32_e32 v232, 31
	v_mov_b32_e32 v233, 0xfff
	v_mov_b32_e32 v234, 0x7ff
	v_not_b32_e32 v235, 63
	v_mov_b32_e32 v237, 0x7fc00000
	s_waitcnt vmcnt(0)
	v_mov_b32_e32 v143, v145
	v_mov_b32_e32 v139, v140
	s_nop 1
	v_permlane16_swap_b32_e32 v145, v143
	v_permlane16_swap_b32_e32 v140, v139
	v_mov_b32_e32 v142, v145
	v_mov_b32_e32 v141, v143
	v_mov_b32_e32 v138, v140
	v_mov_b32_e32 v133, v139
	s_nop 1
	v_permlane32_swap_b32_e32 v145, v142
	v_permlane32_swap_b32_e32 v143, v141
	v_permlane32_swap_b32_e32 v140, v138
	v_permlane32_swap_b32_e32 v139, v133
	s_nop 0
	v_mul_f32_e32 v134, 0x3c800000, v145
	v_pk_mul_f32 v[128:129], v[128:129], v[134:135] op_sel_hi:[1,0]
	v_pk_mul_f32 v[126:127], v[126:127], v[134:135] op_sel_hi:[1,0]
	v_pk_mul_f32 v[124:125], v[124:125], v[134:135] op_sel_hi:[1,0]
	v_pk_mul_f32 v[122:123], v[122:123], v[134:135] op_sel_hi:[1,0]
	s_cbranch_scc0 .LBB0_568
	v_mul_f32_e32 v135, 0xbfb8aa3b, v126
	v_exp_f32_e32 v135, v135
	v_mul_f32_e32 v145, 0xbfb8aa3b, v122
	v_exp_f32_e32 v145, v145
	v_mul_f32_e32 v147, 0xbfb8aa3b, v123
	v_add_f32_e32 v135, 1.0, v135
	v_exp_f32_e32 v148, v147
	v_add_f32_e32 v146, 1.0, v145
	v_rcp_f32_e32 v145, v135
	v_mul_f32_e32 v135, 0xbfb8aa3b, v127
	v_exp_f32_e32 v135, v135
	v_rcp_f32_e32 v146, v146
	s_mov_b64 s[52:53], 0
	v_add_f32_e32 v135, 1.0, v135
	v_rcp_f32_e32 v147, v135
	v_add_f32_e32 v135, 1.0, v148
	v_mul_f32_e32 v148, 0xbfb8aa3b, v128
	v_exp_f32_e32 v149, v148
	v_mul_f32_e32 v148, 0xbfb8aa3b, v124
	v_exp_f32_e32 v150, v148
	v_rcp_f32_e32 v148, v135
	v_add_f32_e32 v135, 1.0, v149
	v_rcp_f32_e32 v149, v135
	v_add_f32_e32 v135, 1.0, v150
	v_mul_f32_e32 v150, 0xbfb8aa3b, v129
	v_exp_f32_e32 v151, v150
	v_mul_f32_e32 v150, 0xbfb8aa3b, v125
	v_exp_f32_e32 v153, v150
	v_rcp_f32_e32 v150, v135
	v_add_f32_e32 v135, 1.0, v151
	v_rcp_f32_e32 v152, v135
	v_add_f32_e32 v135, 1.0, v153
	v_rcp_f32_e32 v151, v135
